# instruction selection: folded the two constant multiplies before v_exp in the GEMM1 gelu epilogue into one (128 VALU per tile-wave)
# baseline (speedup 1.0000x reference)
; DI unsigned cvt_pk_bf16(float lo, float hi) { unsigned r; asm("v_cvt_pk_bf16_f32 %0, %1, %2" : "=v"(r) : "v"(lo), "v"(hi)); return r; }
; DI float gelu_tanh(float x) { const float y = 1.5957691216f * (x + 0.044715f * x * x * x); return x * sigmoidf_(y); }
; DI float sigmoidf_(float x) { return __builtin_amdgcn_rcpf(1.0f + __expf(-x)); }
;     DI void operator()(const AccT& acc, const Unit& u, int wr, int wc, int fr, int fq) const {
;     ...
;             const int col0 = (u.pn - 32) * 256 + wc * 32 + 8 * fq;
; #pragma unroll
;             for (int ai = 0; ai < 2; ++ai)
; #pragma unroll
;                 for (int m = 0; m < 4; ++m)
; #pragma unroll
;                     for (int bj = 0; bj < 2; ++bj) {
;                         float y[8];
; #pragma unroll
;                         for (int n = 0; n < 2; ++n)
; #pragma unroll
;                             for (int j = 0; j < 4; ++j) y[n * 4 + j] = gelu_tanh(acc[ai][bj][m][n][j]);
;                         u32x4 w; w.x = cvt_pk_bf16(y[0], y[1]); w.y = cvt_pk_bf16(y[2], y[3]); w.z = cvt_pk_bf16(y[4], y[5]); w.w = cvt_pk_bf16(y[6], y[7]);
;                         *(u32x4*)(V + (size_t)(row0 + ai * 128 + m * 16) * EI + col0 + bj * 128) = w;
;                     }
.LBB0_164:
	v_fma_f32 v194, v127, v190, v127
	v_mul_f32_e32 v194, 0xc0135761, v194
	v_exp_f32_e32 v194, v194
	v_fma_f32 v195, v116, v189, v116
	v_fma_f32 v196, v117, v188, v117
	v_mul_f32_e32 v195, 0xc0135761, v195
	v_mul_f32_e32 v196, 0xc0135761, v196
	v_add_f32_e32 v194, 1.0, v194
	v_rcp_f32_e32 v194, v194
	v_exp_f32_e32 v195, v195
	v_exp_f32_e32 v196, v196
	v_fma_f32 v158, v125, v192, v125
	v_fma_f32 v159, v126, v191, v126
	v_fma_f32 v138, v124, v193, v124
	v_mul_f32_e32 v158, 0xc0135761, v158
	v_mul_f32_e32 v159, 0xc0135761, v159
	v_mul_f32_e32 v138, 0xc0135761, v138
	v_exp_f32_e32 v158, v158
	v_exp_f32_e32 v159, v159
	v_mul_f32_e32 v197, v127, v194
	v_add_f32_e32 v194, 1.0, v195
	v_add_f32_e32 v195, 1.0, v196
	v_fma_f32 v196, v118, v187, v118
	v_fma_f32 v198, v119, v186, v119
	v_exp_f32_e32 v149, v138
	v_mul_f32_e32 v196, 0xc0135761, v196
	v_mul_f32_e32 v198, 0xc0135761, v198
	v_exp_f32_e32 v196, v196
	v_exp_f32_e32 v198, v198
	v_add_f32_e32 v158, 1.0, v158
	v_add_f32_e32 v159, 1.0, v159
	v_add_f32_e32 v149, 1.0, v149
	v_rcp_f32_e32 v158, v158
	v_rcp_f32_e32 v159, v159
	v_rcp_f32_e32 v149, v149
	v_rcp_f32_e32 v194, v194
	v_rcp_f32_e32 v195, v195
	v_add_f32_e32 v196, 1.0, v196
	v_add_f32_e32 v198, 1.0, v198
	v_rcp_f32_e32 v196, v196
	v_rcp_f32_e32 v198, v198
	v_lshl_add_u32 v138, s94, 8, v162
	v_lshlrev_b64 v[156:157], 13, v[154:155]
	v_mul_f32_e32 v158, v125, v158
	v_mul_f32_e32 v159, v126, v159
	v_mul_f32_e32 v149, v124, v149
	v_mul_f32_e32 v199, v116, v194
	v_mul_f32_e32 v200, v117, v195
	v_cvt_pk_bf16_f32 v194, v149, v158
	v_cvt_pk_bf16_f32 v195, v159, v197
	v_lshl_add_u64 v[156:157], s[14:15], 0, v[156:157]
	v_lshlrev_b64 v[158:159], 1, v[138:139]
	v_lshl_add_u64 v[156:157], v[156:157], 0, v[158:159]
	v_mul_f32_e32 v201, v118, v196
	v_mul_f32_e32 v198, v119, v198
	v_cvt_pk_bf16_f32 v196, v199, v200
	v_cvt_pk_bf16_f32 v197, v201, v198
	global_store_dwordx4 v[156:157], v[194:197], off
	v_mul_f32_e32 v149, 0x3d372713, v120
	v_mul_f32_e32 v149, v120, v149
	v_mul_f32_e32 v194, 0x3d372713, v122
	v_mul_f32_e32 v194, v122, v194
	v_fma_f32 v194, v122, v194, v122
	v_mul_f32_e32 v194, 0xc0135761, v194
	v_exp_f32_e32 v194, v194
	v_mul_f32_e32 v195, 0x3d372713, v123
	v_mul_f32_e32 v195, v123, v195
	v_fma_f32 v195, v123, v195, v123
	v_mul_f32_e32 v195, 0xc0135761, v195
	v_add_f32_e32 v194, 1.0, v194
	v_rcp_f32_e32 v194, v194
	v_exp_f32_e32 v195, v195
	v_mul_f32_e32 v197, 0x3d372713, v113
	v_mul_f32_e32 v197, v113, v197
	v_mul_f32_e32 v196, v122, v194
	v_add_f32_e32 v194, 1.0, v195
	v_mul_f32_e32 v195, 0x3d372713, v112
	v_mul_f32_e32 v195, v112, v195
	v_fma_f32 v149, v120, v149, v120
	v_fma_f32 v195, v112, v195, v112
	v_fma_f32 v197, v113, v197, v113
	v_mul_f32_e32 v149, 0xc0135761, v149
	v_mul_f32_e32 v195, 0xc0135761, v195
	v_mul_f32_e32 v197, 0xc0135761, v197
	v_exp_f32_e32 v149, v149
	v_rcp_f32_e32 v194, v194
	v_exp_f32_e32 v195, v195
	v_exp_f32_e32 v197, v197
	v_add_f32_e32 v138, 1.0, v149
	v_mul_f32_e32 v149, 0x3d372713, v121
	v_mul_f32_e32 v198, v123, v194
	v_add_f32_e32 v194, 1.0, v195
	v_add_f32_e32 v195, 1.0, v197
	v_mul_f32_e32 v197, 0x3d372713, v114
	v_mul_f32_e32 v149, v121, v149
	v_mul_f32_e32 v197, v114, v197
	v_mul_f32_e32 v199, 0x3d372713, v115
	v_fma_f32 v149, v121, v149, v121
	v_fma_f32 v197, v114, v197, v114
	v_mul_f32_e32 v199, v115, v199
	v_mul_f32_e32 v149, 0xc0135761, v149
	v_mul_f32_e32 v197, 0xc0135761, v197
	v_fma_f32 v199, v115, v199, v115
	v_mul_f32_e32 v199, 0xc0135761, v199
	v_exp_f32_e32 v149, v149
	v_exp_f32_e32 v197, v197
	v_exp_f32_e32 v199, v199
	v_add_f32_e32 v149, 1.0, v149
	v_add_f32_e32 v197, 1.0, v197
	v_rcp_f32_e32 v138, v138
	v_rcp_f32_e32 v149, v149
	v_rcp_f32_e32 v194, v194
	v_rcp_f32_e32 v197, v197
	v_add_f32_e32 v199, 1.0, v199
	v_rcp_f32_e32 v195, v195
	v_rcp_f32_e32 v199, v199
	v_mul_f32_e32 v138, v120, v138
	v_mul_f32_e32 v149, v121, v149
	v_mul_f32_e32 v200, v112, v194
	v_mul_f32_e32 v197, v114, v197
	v_cvt_pk_bf16_f32 v194, v138, v149
	v_mul_f32_e32 v201, v113, v195
	v_mul_f32_e32 v199, v115, v199
	v_cvt_pk_bf16_f32 v195, v196, v198
	v_cvt_pk_bf16_f32 v196, v200, v201
	v_cvt_pk_bf16_f32 v197, v197, v199
	global_store_dwordx4 v[156:157], v[194:197], off offset:256
	v_fma_f32 v138, v108, v185, v108
	v_fma_f32 v149, v109, v184, v109
	v_fma_f32 v194, v110, v183, v110
	v_mul_f32_e32 v194, 0xc0135761, v194
	v_exp_f32_e32 v194, v194
	v_fma_f32 v195, v111, v182, v111
	v_mul_f32_e32 v195, 0xc0135761, v195
	v_add_f32_e32 v194, 1.0, v194
	v_rcp_f32_e32 v194, v194
	v_exp_f32_e32 v195, v195
	v_fma_f32 v197, v101, v180, v101
	v_mul_f32_e32 v197, 0xc0135761, v197
	v_mul_f32_e32 v196, v110, v194
	v_add_f32_e32 v194, 1.0, v195
	v_fma_f32 v195, v100, v181, v100
	v_mul_f32_e32 v195, 0xc0135761, v195
	v_rcp_f32_e32 v194, v194
	v_exp_f32_e32 v195, v195
	v_exp_f32_e32 v197, v197
	v_mul_f32_e32 v138, 0xc0135761, v138
	v_mul_f32_e32 v200, v111, v194
	v_add_f32_e32 v194, 1.0, v195
	v_add_f32_e32 v195, 1.0, v197
	v_fma_f32 v197, v102, v179, v102
	v_mul_f32_e32 v149, 0xc0135761, v149
	v_mul_f32_e32 v197, 0xc0135761, v197
	v_fma_f32 v201, v103, v178, v103
	v_mul_f32_e32 v201, 0xc0135761, v201
	v_exp_f32_e32 v138, v138
	v_exp_f32_e32 v149, v149
	v_exp_f32_e32 v197, v197
	v_exp_f32_e32 v201, v201
	v_add_f32_e32 v138, 1.0, v138
	v_add_f32_e32 v149, 1.0, v149
	v_add_f32_e32 v197, 1.0, v197
	v_rcp_f32_e32 v138, v138
	v_rcp_f32_e32 v149, v149
	v_rcp_f32_e32 v194, v194
	v_rcp_f32_e32 v197, v197
	v_add_f32_e32 v201, 1.0, v201
	v_rcp_f32_e32 v195, v195
	v_rcp_f32_e32 v201, v201
	v_lshlrev_b64 v[198:199], 13, v[152:153]
	v_lshl_add_u64 v[198:199], s[14:15], 0, v[198:199]
	v_mul_f32_e32 v138, v108, v138
	v_mul_f32_e32 v149, v109, v149
; DI unsigned cvt_pk_bf16(float lo, float hi) { unsigned r; asm("v_cvt_pk_bf16_f32 %0, %1, %2" : "=v"(r) : "v"(lo), "v"(hi)); return r; }
; DI float gelu_tanh(float x) { const float y = 1.5957691216f * (x + 0.044715f * x * x * x); return x * sigmoidf_(y); }
; DI float sigmoidf_(float x) { return __builtin_amdgcn_rcpf(1.0f + __expf(-x)); }
;     DI void operator()(const AccT& acc, const Unit& u, int wr, int wc, int fr, int fq) const {
;     ...
;             const int col0 = (u.pn - 32) * 256 + wc * 32 + 8 * fq;
; #pragma unroll
;             for (int ai = 0; ai < 2; ++ai)
; #pragma unroll
;                 for (int m = 0; m < 4; ++m)
; #pragma unroll
;                     for (int bj = 0; bj < 2; ++bj) {
;                         float y[8];
; #pragma unroll
;                         for (int n = 0; n < 2; ++n)
; #pragma unroll
;                             for (int j = 0; j < 4; ++j) y[n * 4 + j] = gelu_tanh(acc[ai][bj][m][n][j]);
;                         u32x4 w; w.x = cvt_pk_bf16(y[0], y[1]); w.y = cvt_pk_bf16(y[2], y[3]); w.z = cvt_pk_bf16(y[4], y[5]); w.w = cvt_pk_bf16(y[6], y[7]);
;                         *(u32x4*)(V + (size_t)(row0 + ai * 128 + m * 16) * EI + col0 + bj * 128) = w;
;                     }
	v_mul_f32_e32 v202, v100, v194
	v_mul_f32_e32 v197, v102, v197
	v_cvt_pk_bf16_f32 v194, v138, v149
	v_lshl_add_u64 v[198:199], v[198:199], 0, v[158:159]
	v_mul_f32_e32 v203, v101, v195
	v_mul_f32_e32 v201, v103, v201
	v_cvt_pk_bf16_f32 v195, v196, v200
	v_cvt_pk_bf16_f32 v196, v202, v203
	v_cvt_pk_bf16_f32 v197, v197, v201
	global_store_dwordx4 v[198:199], v[194:197], off
	v_mul_f32_e32 v138, 0x3d372713, v104
	v_mul_f32_e32 v149, 0x3d372713, v105
	v_mul_f32_e32 v194, 0x3d372713, v106
	v_mul_f32_e32 v194, v106, v194
	v_fma_f32 v194, v106, v194, v106
	v_mul_f32_e32 v194, 0xc0135761, v194
	v_exp_f32_e32 v194, v194
	v_mul_f32_e32 v195, 0x3d372713, v107
	v_mul_f32_e32 v195, v107, v195
	v_fma_f32 v195, v107, v195, v107
	v_mul_f32_e32 v195, 0xc0135761, v195
	v_add_f32_e32 v194, 1.0, v194
	v_rcp_f32_e32 v194, v194
	v_exp_f32_e32 v195, v195
	v_mul_f32_e32 v197, 0x3d372713, v97
	v_mul_f32_e32 v197, v97, v197
	v_mul_f32_e32 v196, v106, v194
	v_add_f32_e32 v194, 1.0, v195
	v_mul_f32_e32 v195, 0x3d372713, v96
	v_mul_f32_e32 v195, v96, v195
	v_fma_f32 v195, v96, v195, v96
	v_fma_f32 v197, v97, v197, v97
	v_mul_f32_e32 v195, 0xc0135761, v195
	v_mul_f32_e32 v197, 0xc0135761, v197
	v_rcp_f32_e32 v194, v194
	v_exp_f32_e32 v195, v195
	v_exp_f32_e32 v197, v197
	v_mul_f32_e32 v138, v104, v138
	v_mul_f32_e32 v200, v107, v194
	v_add_f32_e32 v194, 1.0, v195
	v_add_f32_e32 v195, 1.0, v197
	v_mul_f32_e32 v197, 0x3d372713, v98
	v_mul_f32_e32 v149, v105, v149
	v_mul_f32_e32 v197, v98, v197
	v_mul_f32_e32 v201, 0x3d372713, v99
	v_fma_f32 v138, v104, v138, v104
	v_fma_f32 v149, v105, v149, v105
	v_fma_f32 v197, v98, v197, v98
	v_mul_f32_e32 v201, v99, v201
	v_mul_f32_e32 v138, 0xc0135761, v138
	v_mul_f32_e32 v149, 0xc0135761, v149
	v_mul_f32_e32 v197, 0xc0135761, v197
	v_fma_f32 v201, v99, v201, v99
	v_mul_f32_e32 v201, 0xc0135761, v201
	v_exp_f32_e32 v138, v138
	v_exp_f32_e32 v149, v149
	v_exp_f32_e32 v197, v197
	v_exp_f32_e32 v201, v201
	v_add_f32_e32 v138, 1.0, v138
	v_add_f32_e32 v149, 1.0, v149
	v_add_f32_e32 v197, 1.0, v197
	v_rcp_f32_e32 v138, v138
	v_rcp_f32_e32 v149, v149
	v_rcp_f32_e32 v194, v194
	v_rcp_f32_e32 v197, v197
	v_add_f32_e32 v201, 1.0, v201
	v_rcp_f32_e32 v195, v195
	v_rcp_f32_e32 v201, v201
	v_mul_f32_e32 v138, v104, v138
	v_mul_f32_e32 v149, v105, v149
	v_mul_f32_e32 v202, v96, v194
	v_mul_f32_e32 v197, v98, v197
	v_cvt_pk_bf16_f32 v194, v138, v149
	v_mul_f32_e32 v203, v97, v195
	v_mul_f32_e32 v201, v99, v201
	v_cvt_pk_bf16_f32 v195, v196, v200
	v_cvt_pk_bf16_f32 v196, v202, v203
	v_cvt_pk_bf16_f32 v197, v197, v201
	global_store_dwordx4 v[198:199], v[194:197], off offset:256
	v_fma_f32 v138, v92, v177, v92
	v_fma_f32 v149, v93, v176, v93
	v_fma_f32 v194, v94, v175, v94
	v_mul_f32_e32 v194, 0xc0135761, v194
	v_exp_f32_e32 v194, v194
	v_fma_f32 v195, v95, v174, v95
	v_mul_f32_e32 v195, 0xc0135761, v195
	v_add_f32_e32 v194, 1.0, v194
	v_rcp_f32_e32 v194, v194
	v_exp_f32_e32 v195, v195
	v_fma_f32 v197, v85, v172, v85
	v_mul_f32_e32 v197, 0xc0135761, v197
	v_mul_f32_e32 v196, v94, v194
	v_add_f32_e32 v194, 1.0, v195
	v_fma_f32 v195, v84, v173, v84
	v_mul_f32_e32 v195, 0xc0135761, v195
	v_rcp_f32_e32 v194, v194
	v_exp_f32_e32 v195, v195
	v_exp_f32_e32 v197, v197
	v_mul_f32_e32 v138, 0xc0135761, v138
	v_mul_f32_e32 v200, v95, v194
	v_add_f32_e32 v194, 1.0, v195
	v_add_f32_e32 v195, 1.0, v197
	v_fma_f32 v197, v86, v171, v86
	v_mul_f32_e32 v149, 0xc0135761, v149
	v_mul_f32_e32 v197, 0xc0135761, v197
	v_fma_f32 v201, v87, v170, v87
	v_mul_f32_e32 v201, 0xc0135761, v201
	v_exp_f32_e32 v138, v138
	v_exp_f32_e32 v149, v149
	v_exp_f32_e32 v197, v197
	v_exp_f32_e32 v201, v201
	v_add_f32_e32 v138, 1.0, v138
	v_add_f32_e32 v149, 1.0, v149
	v_add_f32_e32 v197, 1.0, v197
	v_rcp_f32_e32 v138, v138
	v_rcp_f32_e32 v149, v149
	v_rcp_f32_e32 v194, v194
	v_rcp_f32_e32 v197, v197
	v_add_f32_e32 v201, 1.0, v201
	v_rcp_f32_e32 v195, v195
	v_rcp_f32_e32 v201, v201
	v_lshlrev_b64 v[198:199], 13, v[150:151]
	v_lshl_add_u64 v[198:199], s[14:15], 0, v[198:199]
	v_mul_f32_e32 v138, v92, v138
	v_mul_f32_e32 v149, v93, v149
	v_mul_f32_e32 v202, v84, v194
	v_mul_f32_e32 v197, v86, v197
	v_cvt_pk_bf16_f32 v194, v138, v149
	v_lshl_add_u64 v[198:199], v[198:199], 0, v[158:159]
	v_mul_f32_e32 v203, v85, v195
	v_mul_f32_e32 v201, v87, v201
	v_cvt_pk_bf16_f32 v195, v196, v200
	v_cvt_pk_bf16_f32 v196, v202, v203
	v_cvt_pk_bf16_f32 v197, v197, v201
	global_store_dwordx4 v[198:199], v[194:197], off
	v_mul_f32_e32 v138, 0x3d372713, v88
	v_mul_f32_e32 v149, 0x3d372713, v89
	v_mul_f32_e32 v194, 0x3d372713, v90
	v_mul_f32_e32 v194, v90, v194
	v_fma_f32 v194, v90, v194, v90
	v_mul_f32_e32 v194, 0xc0135761, v194
	v_exp_f32_e32 v194, v194
	v_mul_f32_e32 v195, 0x3d372713, v91
	v_mul_f32_e32 v195, v91, v195
	v_fma_f32 v195, v91, v195, v91
	v_mul_f32_e32 v195, 0xc0135761, v195
	v_add_f32_e32 v194, 1.0, v194
	v_rcp_f32_e32 v194, v194
	v_exp_f32_e32 v195, v195
	v_mul_f32_e32 v197, 0x3d372713, v81
	v_mul_f32_e32 v197, v81, v197
	v_mul_f32_e32 v196, v90, v194
	v_add_f32_e32 v194, 1.0, v195
	v_mul_f32_e32 v195, 0x3d372713, v80
	v_mul_f32_e32 v195, v80, v195
	v_fma_f32 v195, v80, v195, v80
	v_fma_f32 v197, v81, v197, v81
	v_mul_f32_e32 v195, 0xc0135761, v195
	v_mul_f32_e32 v197, 0xc0135761, v197
	v_rcp_f32_e32 v194, v194
	v_exp_f32_e32 v195, v195
	v_exp_f32_e32 v197, v197
	v_mul_f32_e32 v138, v88, v138
	v_mul_f32_e32 v200, v91, v194
	v_add_f32_e32 v194, 1.0, v195
	v_add_f32_e32 v195, 1.0, v197
	v_mul_f32_e32 v197, 0x3d372713, v82
	v_mul_f32_e32 v149, v89, v149
	v_mul_f32_e32 v197, v82, v197
	v_mul_f32_e32 v201, 0x3d372713, v83
	v_fma_f32 v138, v88, v138, v88
	v_fma_f32 v149, v89, v149, v89
; DI unsigned cvt_pk_bf16(float lo, float hi) { unsigned r; asm("v_cvt_pk_bf16_f32 %0, %1, %2" : "=v"(r) : "v"(lo), "v"(hi)); return r; }
; DI float gelu_tanh(float x) { const float y = 1.5957691216f * (x + 0.044715f * x * x * x); return x * sigmoidf_(y); }
; DI float sigmoidf_(float x) { return __builtin_amdgcn_rcpf(1.0f + __expf(-x)); }
;     DI void operator()(const AccT& acc, const Unit& u, int wr, int wc, int fr, int fq) const {
;     ...
;             const int col0 = (u.pn - 32) * 256 + wc * 32 + 8 * fq;
; #pragma unroll
;             for (int ai = 0; ai < 2; ++ai)
; #pragma unroll
;                 for (int m = 0; m < 4; ++m)
; #pragma unroll
;                     for (int bj = 0; bj < 2; ++bj) {
;                         float y[8];
; #pragma unroll
;                         for (int n = 0; n < 2; ++n)
; #pragma unroll
;                             for (int j = 0; j < 4; ++j) y[n * 4 + j] = gelu_tanh(acc[ai][bj][m][n][j]);
;                         u32x4 w; w.x = cvt_pk_bf16(y[0], y[1]); w.y = cvt_pk_bf16(y[2], y[3]); w.z = cvt_pk_bf16(y[4], y[5]); w.w = cvt_pk_bf16(y[6], y[7]);
;                         *(u32x4*)(V + (size_t)(row0 + ai * 128 + m * 16) * EI + col0 + bj * 128) = w;
;                     }
	v_fma_f32 v197, v82, v197, v82
	v_mul_f32_e32 v201, v83, v201
	v_mul_f32_e32 v138, 0xc0135761, v138
	v_mul_f32_e32 v149, 0xc0135761, v149
	v_mul_f32_e32 v197, 0xc0135761, v197
	v_fma_f32 v201, v83, v201, v83
	v_mul_f32_e32 v201, 0xc0135761, v201
	v_exp_f32_e32 v138, v138
	v_exp_f32_e32 v149, v149
	v_exp_f32_e32 v197, v197
	v_exp_f32_e32 v201, v201
	v_add_f32_e32 v138, 1.0, v138
	v_add_f32_e32 v149, 1.0, v149
	v_add_f32_e32 v197, 1.0, v197
	v_rcp_f32_e32 v138, v138
	v_rcp_f32_e32 v149, v149
	v_rcp_f32_e32 v194, v194
	v_rcp_f32_e32 v197, v197
	v_add_f32_e32 v201, 1.0, v201
	v_rcp_f32_e32 v195, v195
	v_rcp_f32_e32 v201, v201
	v_mul_f32_e32 v138, v88, v138
	v_mul_f32_e32 v149, v89, v149
	v_mul_f32_e32 v202, v80, v194
	v_mul_f32_e32 v197, v82, v197
	v_cvt_pk_bf16_f32 v194, v138, v149
	v_mul_f32_e32 v203, v81, v195
	v_mul_f32_e32 v201, v83, v201
	v_cvt_pk_bf16_f32 v195, v196, v200
	v_cvt_pk_bf16_f32 v196, v202, v203
	v_cvt_pk_bf16_f32 v197, v197, v201
	global_store_dwordx4 v[198:199], v[194:197], off offset:256
	v_ashrrev_i32_e32 v149, 31, v148
	v_mul_f32_e32 v138, v76, v169
	v_mul_f32_e32 v194, v78, v167
	v_fma_f32 v194, v78, v194, v78
	v_mul_f32_e32 v194, 0xc0135761, v194
	v_exp_f32_e32 v194, v194
	v_mul_f32_e32 v195, v79, v166
	v_fma_f32 v195, v79, v195, v79
	v_mul_f32_e32 v195, 0xc0135761, v195
	v_add_f32_e32 v194, 1.0, v194
	v_rcp_f32_e32 v194, v194
	v_exp_f32_e32 v195, v195
	v_mul_f32_e32 v197, 0x3d372713, v69
	v_mul_f32_e32 v197, v69, v197
	v_mul_f32_e32 v196, v78, v194
	v_add_f32_e32 v194, 1.0, v195
	v_mul_f32_e32 v195, 0x3d372713, v68
	v_mul_f32_e32 v195, v68, v195
	v_fma_f32 v195, v68, v195, v68
	v_fma_f32 v197, v69, v197, v69
	v_mul_f32_e32 v195, 0xc0135761, v195
	v_mul_f32_e32 v197, 0xc0135761, v197
	v_rcp_f32_e32 v194, v194
	v_exp_f32_e32 v195, v195
	v_exp_f32_e32 v197, v197
	v_lshlrev_b64 v[198:199], 13, v[148:149]
	v_mul_f32_e32 v200, v79, v194
	v_add_f32_e32 v194, 1.0, v195
	v_add_f32_e32 v195, 1.0, v197
	v_mul_f32_e32 v197, 0x3d372713, v70
	v_mul_f32_e32 v149, v77, v168
	v_mul_f32_e32 v197, v70, v197
	v_mul_f32_e32 v201, 0x3d372713, v71
	v_fma_f32 v138, v76, v138, v76
	v_fma_f32 v149, v77, v149, v77
	v_fma_f32 v197, v70, v197, v70
	v_mul_f32_e32 v201, v71, v201
	v_mul_f32_e32 v138, 0xc0135761, v138
	v_mul_f32_e32 v149, 0xc0135761, v149
	v_mul_f32_e32 v197, 0xc0135761, v197
	v_fma_f32 v201, v71, v201, v71
	v_mul_f32_e32 v201, 0xc0135761, v201
	v_exp_f32_e32 v138, v138
	v_exp_f32_e32 v149, v149
	v_exp_f32_e32 v197, v197
	v_exp_f32_e32 v201, v201
	v_add_f32_e32 v138, 1.0, v138
	v_add_f32_e32 v149, 1.0, v149
	v_add_f32_e32 v197, 1.0, v197
	v_rcp_f32_e32 v138, v138
	v_rcp_f32_e32 v149, v149
	v_rcp_f32_e32 v194, v194
	v_rcp_f32_e32 v197, v197
	v_add_f32_e32 v201, 1.0, v201
	v_rcp_f32_e32 v195, v195
	v_rcp_f32_e32 v201, v201
	v_lshl_add_u64 v[198:199], s[14:15], 0, v[198:199]
	v_mul_f32_e32 v138, v76, v138
	v_mul_f32_e32 v149, v77, v149
	v_mul_f32_e32 v202, v68, v194
	v_mul_f32_e32 v197, v70, v197
	v_cvt_pk_bf16_f32 v194, v138, v149
	v_lshl_add_u64 v[158:159], v[198:199], 0, v[158:159]
	v_mul_f32_e32 v203, v69, v195
	v_mul_f32_e32 v201, v71, v201
	v_cvt_pk_bf16_f32 v195, v196, v200
	v_cvt_pk_bf16_f32 v196, v202, v203
	v_cvt_pk_bf16_f32 v197, v197, v201
	global_store_dwordx4 v[158:159], v[194:197], off
	v_mul_f32_e32 v138, 0x3d372713, v72
	v_mul_f32_e32 v149, 0x3d372713, v73
	v_mul_f32_e32 v194, 0x3d372713, v74
	v_mul_f32_e32 v194, v74, v194
	v_fma_f32 v194, v74, v194, v74
	v_mul_f32_e32 v194, 0xc0135761, v194
	v_exp_f32_e32 v194, v194
	v_mul_f32_e32 v195, 0x3d372713, v75
	v_mul_f32_e32 v195, v75, v195
	v_fma_f32 v195, v75, v195, v75
	v_mul_f32_e32 v195, 0xc0135761, v195
	v_add_f32_e32 v194, 1.0, v194
	v_rcp_f32_e32 v194, v194
	v_exp_f32_e32 v195, v195
	v_mul_f32_e32 v197, 0x3d372713, v65
	v_mul_f32_e32 v197, v65, v197
	v_mul_f32_e32 v196, v74, v194
	v_add_f32_e32 v194, 1.0, v195
	v_mul_f32_e32 v195, 0x3d372713, v64
	v_mul_f32_e32 v195, v64, v195
	v_fma_f32 v195, v64, v195, v64
	v_fma_f32 v197, v65, v197, v65
	v_mul_f32_e32 v195, 0xc0135761, v195
	v_mul_f32_e32 v197, 0xc0135761, v197
	v_rcp_f32_e32 v194, v194
	v_exp_f32_e32 v195, v195
	v_exp_f32_e32 v197, v197
	v_mul_f32_e32 v138, v72, v138
	v_mul_f32_e32 v198, v75, v194
	v_add_f32_e32 v194, 1.0, v195
	v_add_f32_e32 v195, 1.0, v197
	v_mul_f32_e32 v197, 0x3d372713, v66
	v_mul_f32_e32 v149, v73, v149
	v_mul_f32_e32 v197, v66, v197
	v_mul_f32_e32 v199, 0x3d372713, v67
	v_fma_f32 v138, v72, v138, v72
	v_fma_f32 v149, v73, v149, v73
	v_fma_f32 v197, v66, v197, v66
	v_mul_f32_e32 v199, v67, v199
	v_mul_f32_e32 v138, 0xc0135761, v138
	v_mul_f32_e32 v149, 0xc0135761, v149
	v_mul_f32_e32 v197, 0xc0135761, v197
	v_fma_f32 v199, v67, v199, v67
	v_mul_f32_e32 v199, 0xc0135761, v199
	v_exp_f32_e32 v138, v138
	v_exp_f32_e32 v149, v149
	v_exp_f32_e32 v197, v197
	v_exp_f32_e32 v199, v199
	v_add_f32_e32 v138, 1.0, v138
	v_add_f32_e32 v149, 1.0, v149
	v_add_f32_e32 v197, 1.0, v197
	v_rcp_f32_e32 v138, v138
	v_rcp_f32_e32 v149, v149
	v_rcp_f32_e32 v194, v194
	v_rcp_f32_e32 v197, v197
	v_add_f32_e32 v199, 1.0, v199
	v_rcp_f32_e32 v195, v195
	v_rcp_f32_e32 v199, v199
	v_mul_f32_e32 v138, v72, v138
	v_mul_f32_e32 v149, v73, v149
	v_mul_f32_e32 v200, v64, v194
	v_mul_f32_e32 v197, v66, v197
	v_cvt_pk_bf16_f32 v194, v138, v149
	v_mul_f32_e32 v201, v65, v195
	v_mul_f32_e32 v199, v67, v199
	v_cvt_pk_bf16_f32 v195, v196, v198
	v_cvt_pk_bf16_f32 v196, v200, v201
	v_cvt_pk_bf16_f32 v197, v197, v199
	global_store_dwordx4 v[158:159], v[194:197], off offset:256
	v_mul_f32_e32 v138, 0x3d372713, v60
	v_mul_f32_e32 v149, 0x3d372713, v61
	v_mul_f32_e32 v194, 0x3d372713, v52
	v_mul_f32_e32 v194, v52, v194
; DI unsigned cvt_pk_bf16(float lo, float hi) { unsigned r; asm("v_cvt_pk_bf16_f32 %0, %1, %2" : "=v"(r) : "v"(lo), "v"(hi)); return r; }
; DI float gelu_tanh(float x) { const float y = 1.5957691216f * (x + 0.044715f * x * x * x); return x * sigmoidf_(y); }
; DI float sigmoidf_(float x) { return __builtin_amdgcn_rcpf(1.0f + __expf(-x)); }
;     DI void operator()(const AccT& acc, const Unit& u, int wr, int wc, int fr, int fq) const {
;     ...
;             const int col0 = (u.pn - 32) * 256 + wc * 32 + 8 * fq;
; #pragma unroll
;             for (int ai = 0; ai < 2; ++ai)
; #pragma unroll
;                 for (int m = 0; m < 4; ++m)
; #pragma unroll
;                     for (int bj = 0; bj < 2; ++bj) {
;                         float y[8];
; #pragma unroll
;                         for (int n = 0; n < 2; ++n)
; #pragma unroll
;                             for (int j = 0; j < 4; ++j) y[n * 4 + j] = gelu_tanh(acc[ai][bj][m][n][j]);
;                         u32x4 w; w.x = cvt_pk_bf16(y[0], y[1]); w.y = cvt_pk_bf16(y[2], y[3]); w.z = cvt_pk_bf16(y[4], y[5]); w.w = cvt_pk_bf16(y[6], y[7]);
;                         *(u32x4*)(V + (size_t)(row0 + ai * 128 + m * 16) * EI + col0 + bj * 128) = w;
;                     }
	v_mul_f32_e32 v195, 0x3d372713, v53
	v_mul_f32_e32 v196, 0x3d372713, v54
	v_fma_f32 v194, v52, v194, v52
	v_mul_f32_e32 v195, v53, v195
	v_mul_f32_e32 v196, v54, v196
	v_mul_f32_e32 v197, 0x3d372713, v55
	v_mul_f32_e32 v138, v60, v138
	v_mul_f32_e32 v149, v61, v149
	v_mul_f32_e32 v158, 0x3d372713, v62
	v_mul_f32_e32 v159, 0x3d372713, v63
	v_mul_f32_e32 v194, 0xc0135761, v194
	v_fma_f32 v195, v53, v195, v53
	v_fma_f32 v196, v54, v196, v54
	v_mul_f32_e32 v197, v55, v197
	v_fma_f32 v138, v60, v138, v60
	v_fma_f32 v149, v61, v149, v61
	v_mul_f32_e32 v158, v62, v158
	v_mul_f32_e32 v159, v63, v159
	v_mul_f32_e32 v195, 0xc0135761, v195
	v_mul_f32_e32 v196, 0xc0135761, v196
	v_fma_f32 v197, v55, v197, v55
	v_mul_f32_e32 v138, 0xc0135761, v138
	v_mul_f32_e32 v149, 0xc0135761, v149
	v_fma_f32 v158, v62, v158, v62
	v_fma_f32 v159, v63, v159, v63
	v_exp_f32_e32 v194, v194
	v_mul_f32_e32 v197, 0xc0135761, v197
	v_mul_f32_e32 v158, 0xc0135761, v158
	v_mul_f32_e32 v159, 0xc0135761, v159
	v_exp_f32_e32 v195, v195
	v_exp_f32_e32 v196, v196
	v_exp_f32_e32 v138, v138
	v_exp_f32_e32 v149, v149
	v_exp_f32_e32 v197, v197
	v_exp_f32_e32 v158, v158
	v_exp_f32_e32 v159, v159
	v_add_f32_e32 v194, 1.0, v194
	v_rcp_f32_e32 v194, v194
	v_add_f32_e32 v195, 1.0, v195
	v_add_f32_e32 v196, 1.0, v196
	v_add_f32_e32 v138, 1.0, v138
	v_add_f32_e32 v149, 1.0, v149
	v_rcp_f32_e32 v195, v195
	v_rcp_f32_e32 v196, v196
	v_add_f32_e32 v197, 1.0, v197
	v_rcp_f32_e32 v138, v138
	v_rcp_f32_e32 v149, v149
	v_add_f32_e32 v158, 1.0, v158
	v_add_f32_e32 v159, 1.0, v159
	v_rcp_f32_e32 v197, v197
	v_rcp_f32_e32 v158, v158
	v_rcp_f32_e32 v159, v159
	v_mul_f32_e32 v198, v52, v194
	v_mul_f32_e32 v199, v53, v195
	v_mul_f32_e32 v200, v54, v196
	v_cvt_pk_bf16_f32 v196, v198, v199
	v_add_co_u32_e32 v198, vcc, s89, v156
	v_mul_f32_e32 v138, v60, v138
	v_mul_f32_e32 v149, v61, v149
	v_mul_f32_e32 v197, v55, v197
	v_cvt_pk_bf16_f32 v194, v138, v149
	v_addc_co_u32_e32 v199, vcc, 0, v157, vcc
	v_mul_f32_e32 v158, v62, v158
	v_mul_f32_e32 v159, v63, v159
	v_cvt_pk_bf16_f32 v195, v158, v159
	v_cvt_pk_bf16_f32 v197, v200, v197
	global_store_dwordx4 v[198:199], v[194:197], off
	v_mul_f32_e32 v138, 0x3d372713, v56
	v_mul_f32_e32 v149, 0x3d372713, v57
	v_mul_f32_e32 v194, 0x3d372713, v58
	v_mul_f32_e32 v194, v58, v194
	v_fma_f32 v194, v58, v194, v58
	v_mul_f32_e32 v194, 0xc0135761, v194
	v_exp_f32_e32 v194, v194
	v_mul_f32_e32 v195, 0x3d372713, v59
	v_mul_f32_e32 v195, v59, v195
	v_fma_f32 v195, v59, v195, v59
	v_mul_f32_e32 v195, 0xc0135761, v195
	v_add_f32_e32 v194, 1.0, v194
	v_rcp_f32_e32 v194, v194
	v_exp_f32_e32 v195, v195
	v_mul_f32_e32 v197, 0x3d372713, v49
	v_mul_f32_e32 v197, v49, v197
	v_mul_f32_e32 v196, v58, v194
	v_add_f32_e32 v194, 1.0, v195
	v_mul_f32_e32 v195, 0x3d372713, v48
	v_mul_f32_e32 v195, v48, v195
	v_fma_f32 v195, v48, v195, v48
	v_fma_f32 v197, v49, v197, v49
	v_mul_f32_e32 v195, 0xc0135761, v195
	v_mul_f32_e32 v197, 0xc0135761, v197
	v_rcp_f32_e32 v194, v194
	v_exp_f32_e32 v195, v195
	v_exp_f32_e32 v197, v197
	v_mul_f32_e32 v138, v56, v138
	v_mul_f32_e32 v198, v59, v194
	v_add_f32_e32 v194, 1.0, v195
	v_add_f32_e32 v195, 1.0, v197
	v_mul_f32_e32 v197, 0x3d372713, v50
	v_mul_f32_e32 v149, v57, v149
	v_mul_f32_e32 v197, v50, v197
	v_mul_f32_e32 v199, 0x3d372713, v51
	v_fma_f32 v138, v56, v138, v56
	v_fma_f32 v149, v57, v149, v57
	v_fma_f32 v197, v50, v197, v50
	v_mul_f32_e32 v199, v51, v199
	v_mul_f32_e32 v138, 0xc0135761, v138
	v_mul_f32_e32 v149, 0xc0135761, v149
	v_mul_f32_e32 v197, 0xc0135761, v197
	v_fma_f32 v199, v51, v199, v51
	v_mul_f32_e32 v199, 0xc0135761, v199
	v_exp_f32_e32 v138, v138
	v_exp_f32_e32 v149, v149
	v_exp_f32_e32 v197, v197
	v_exp_f32_e32 v199, v199
	v_add_f32_e32 v138, 1.0, v138
	v_add_f32_e32 v149, 1.0, v149
	v_add_f32_e32 v197, 1.0, v197
	v_rcp_f32_e32 v138, v138
	v_rcp_f32_e32 v149, v149
	v_rcp_f32_e32 v194, v194
	v_rcp_f32_e32 v197, v197
	v_add_f32_e32 v199, 1.0, v199
	v_rcp_f32_e32 v195, v195
	v_rcp_f32_e32 v199, v199
	v_lshl_add_u64 v[158:159], v[156:157], 0, s[22:23]
	v_mul_f32_e32 v138, v56, v138
	v_mul_f32_e32 v149, v57, v149
	v_mul_f32_e32 v200, v48, v194
	v_mul_f32_e32 v197, v50, v197
	v_cvt_pk_bf16_f32 v194, v138, v149
	v_mul_f32_e32 v201, v49, v195
	v_mul_f32_e32 v199, v51, v199
	v_cvt_pk_bf16_f32 v195, v196, v198
	v_cvt_pk_bf16_f32 v196, v200, v201
	v_cvt_pk_bf16_f32 v197, v197, v199
	global_store_dwordx4 v[158:159], v[194:197], off offset:256
	v_mul_f32_e32 v138, 0x3d372713, v44
	v_mul_f32_e32 v149, 0x3d372713, v45
	v_mul_f32_e32 v194, 0x3d372713, v36
	v_mul_f32_e32 v194, v36, v194
	v_mul_f32_e32 v195, 0x3d372713, v37
	v_mul_f32_e32 v196, 0x3d372713, v38
	v_fma_f32 v194, v36, v194, v36
	v_mul_f32_e32 v195, v37, v195
	v_mul_f32_e32 v196, v38, v196
	v_mul_f32_e32 v197, 0x3d372713, v39
	v_mul_f32_e32 v138, v44, v138
	v_mul_f32_e32 v149, v45, v149
	v_mul_f32_e32 v158, 0x3d372713, v46
	v_mul_f32_e32 v159, 0x3d372713, v47
	v_mul_f32_e32 v194, 0xc0135761, v194
	v_fma_f32 v195, v37, v195, v37
	v_fma_f32 v196, v38, v196, v38
	v_mul_f32_e32 v197, v39, v197
	v_fma_f32 v138, v44, v138, v44
	v_fma_f32 v149, v45, v149, v45
	v_mul_f32_e32 v158, v46, v158
	v_mul_f32_e32 v159, v47, v159
	v_mul_f32_e32 v195, 0xc0135761, v195
	v_mul_f32_e32 v196, 0xc0135761, v196
	v_fma_f32 v197, v39, v197, v39
	v_mul_f32_e32 v138, 0xc0135761, v138
	v_mul_f32_e32 v149, 0xc0135761, v149
	v_fma_f32 v158, v46, v158, v46
	v_fma_f32 v159, v47, v159, v47
	v_exp_f32_e32 v194, v194
	v_mul_f32_e32 v197, 0xc0135761, v197
	v_mul_f32_e32 v158, 0xc0135761, v158
	v_mul_f32_e32 v159, 0xc0135761, v159
	v_exp_f32_e32 v195, v195
	v_exp_f32_e32 v196, v196
	v_exp_f32_e32 v138, v138
; DI unsigned cvt_pk_bf16(float lo, float hi) { unsigned r; asm("v_cvt_pk_bf16_f32 %0, %1, %2" : "=v"(r) : "v"(lo), "v"(hi)); return r; }
; DI float gelu_tanh(float x) { const float y = 1.5957691216f * (x + 0.044715f * x * x * x); return x * sigmoidf_(y); }
; DI float sigmoidf_(float x) { return __builtin_amdgcn_rcpf(1.0f + __expf(-x)); }
;     DI void operator()(const AccT& acc, const Unit& u, int wr, int wc, int fr, int fq) const {
;     ...
;             const int col0 = (u.pn - 32) * 256 + wc * 32 + 8 * fq;
; #pragma unroll
;             for (int ai = 0; ai < 2; ++ai)
; #pragma unroll
;                 for (int m = 0; m < 4; ++m)
; #pragma unroll
;                     for (int bj = 0; bj < 2; ++bj) {
;                         float y[8];
; #pragma unroll
;                         for (int n = 0; n < 2; ++n)
; #pragma unroll
;                             for (int j = 0; j < 4; ++j) y[n * 4 + j] = gelu_tanh(acc[ai][bj][m][n][j]);
;                         u32x4 w; w.x = cvt_pk_bf16(y[0], y[1]); w.y = cvt_pk_bf16(y[2], y[3]); w.z = cvt_pk_bf16(y[4], y[5]); w.w = cvt_pk_bf16(y[6], y[7]);
;                         *(u32x4*)(V + (size_t)(row0 + ai * 128 + m * 16) * EI + col0 + bj * 128) = w;
;                     }
	v_exp_f32_e32 v149, v149
	v_exp_f32_e32 v197, v197
	v_exp_f32_e32 v158, v158
	v_exp_f32_e32 v159, v159
	v_add_f32_e32 v194, 1.0, v194
	v_rcp_f32_e32 v194, v194
	v_add_f32_e32 v195, 1.0, v195
	v_add_f32_e32 v196, 1.0, v196
	v_add_f32_e32 v138, 1.0, v138
	v_add_f32_e32 v149, 1.0, v149
	v_rcp_f32_e32 v195, v195
	v_rcp_f32_e32 v196, v196
	v_add_f32_e32 v197, 1.0, v197
	v_rcp_f32_e32 v138, v138
	v_rcp_f32_e32 v149, v149
	v_add_f32_e32 v158, 1.0, v158
	v_add_f32_e32 v159, 1.0, v159
	v_rcp_f32_e32 v197, v197
	v_rcp_f32_e32 v158, v158
	v_rcp_f32_e32 v159, v159
	v_mul_f32_e32 v198, v36, v194
	v_mul_f32_e32 v199, v37, v195
	v_mul_f32_e32 v200, v38, v196
	v_cvt_pk_bf16_f32 v196, v198, v199
	v_add_co_u32_e32 v198, vcc, s91, v156
	v_mul_f32_e32 v138, v44, v138
	v_mul_f32_e32 v149, v45, v149
	v_mul_f32_e32 v197, v39, v197
	v_cvt_pk_bf16_f32 v194, v138, v149
	v_addc_co_u32_e32 v199, vcc, 0, v157, vcc
	v_mul_f32_e32 v158, v46, v158
	v_mul_f32_e32 v159, v47, v159
	v_cvt_pk_bf16_f32 v195, v158, v159
	v_cvt_pk_bf16_f32 v197, v200, v197
	global_store_dwordx4 v[198:199], v[194:197], off
	v_mul_f32_e32 v138, 0x3d372713, v40
	v_mul_f32_e32 v149, 0x3d372713, v41
	v_mul_f32_e32 v194, 0x3d372713, v42
	v_mul_f32_e32 v194, v42, v194
	v_fma_f32 v194, v42, v194, v42
	v_mul_f32_e32 v194, 0xc0135761, v194
	v_exp_f32_e32 v194, v194
	v_mul_f32_e32 v195, 0x3d372713, v43
	v_mul_f32_e32 v195, v43, v195
	v_fma_f32 v195, v43, v195, v43
	v_mul_f32_e32 v195, 0xc0135761, v195
	v_add_f32_e32 v194, 1.0, v194
	v_rcp_f32_e32 v194, v194
	v_exp_f32_e32 v195, v195
	v_mul_f32_e32 v197, 0x3d372713, v33
	v_mul_f32_e32 v197, v33, v197
	v_mul_f32_e32 v196, v42, v194
	v_add_f32_e32 v194, 1.0, v195
	v_mul_f32_e32 v195, 0x3d372713, v32
	v_mul_f32_e32 v195, v32, v195
	v_fma_f32 v195, v32, v195, v32
	v_fma_f32 v197, v33, v197, v33
	v_mul_f32_e32 v195, 0xc0135761, v195
	v_mul_f32_e32 v197, 0xc0135761, v197
	v_rcp_f32_e32 v194, v194
	v_exp_f32_e32 v195, v195
	v_exp_f32_e32 v197, v197
	v_mul_f32_e32 v138, v40, v138
	v_mul_f32_e32 v198, v43, v194
	v_add_f32_e32 v194, 1.0, v195
	v_add_f32_e32 v195, 1.0, v197
	v_mul_f32_e32 v197, 0x3d372713, v34
	v_mul_f32_e32 v149, v41, v149
	v_mul_f32_e32 v197, v34, v197
	v_mul_f32_e32 v199, 0x3d372713, v35
	v_fma_f32 v138, v40, v138, v40
	v_fma_f32 v149, v41, v149, v41
	v_fma_f32 v197, v34, v197, v34
	v_mul_f32_e32 v199, v35, v199
	v_mul_f32_e32 v138, 0xc0135761, v138
	v_mul_f32_e32 v149, 0xc0135761, v149
	v_mul_f32_e32 v197, 0xc0135761, v197
	v_fma_f32 v199, v35, v199, v35
	v_mul_f32_e32 v199, 0xc0135761, v199
	v_exp_f32_e32 v138, v138
	v_exp_f32_e32 v149, v149
	v_exp_f32_e32 v197, v197
	v_exp_f32_e32 v199, v199
	v_add_f32_e32 v138, 1.0, v138
	v_add_f32_e32 v149, 1.0, v149
	v_add_f32_e32 v197, 1.0, v197
	v_rcp_f32_e32 v138, v138
	v_rcp_f32_e32 v149, v149
	v_rcp_f32_e32 v194, v194
	v_rcp_f32_e32 v197, v197
	v_add_f32_e32 v199, 1.0, v199
	v_rcp_f32_e32 v195, v195
	v_rcp_f32_e32 v199, v199
	v_lshl_add_u64 v[158:159], v[156:157], 0, s[24:25]
	v_mul_f32_e32 v138, v40, v138
	v_mul_f32_e32 v149, v41, v149
	v_mul_f32_e32 v200, v32, v194
	v_mul_f32_e32 v197, v34, v197
	v_cvt_pk_bf16_f32 v194, v138, v149
	v_mul_f32_e32 v201, v33, v195
	v_mul_f32_e32 v199, v35, v199
	v_cvt_pk_bf16_f32 v195, v196, v198
	v_cvt_pk_bf16_f32 v196, v200, v201
	v_cvt_pk_bf16_f32 v197, v197, v199
	global_store_dwordx4 v[158:159], v[194:197], off offset:256
	v_mul_f32_e32 v138, 0x3d372713, v28
	v_mul_f32_e32 v149, 0x3d372713, v29
	v_mul_f32_e32 v194, 0x3d372713, v20
	v_mul_f32_e32 v194, v20, v194
	v_mul_f32_e32 v195, 0x3d372713, v21
	v_mul_f32_e32 v196, 0x3d372713, v22
	v_fma_f32 v194, v20, v194, v20
	v_mul_f32_e32 v195, v21, v195
	v_mul_f32_e32 v196, v22, v196
	v_mul_f32_e32 v197, 0x3d372713, v23
	v_mul_f32_e32 v138, v28, v138
	v_mul_f32_e32 v149, v29, v149
	v_mul_f32_e32 v158, 0x3d372713, v30
	v_mul_f32_e32 v159, 0x3d372713, v31
	v_mul_f32_e32 v194, 0xc0135761, v194
	v_fma_f32 v195, v21, v195, v21
	v_fma_f32 v196, v22, v196, v22
	v_mul_f32_e32 v197, v23, v197
	v_fma_f32 v138, v28, v138, v28
	v_fma_f32 v149, v29, v149, v29
	v_mul_f32_e32 v158, v30, v158
	v_mul_f32_e32 v159, v31, v159
	v_mul_f32_e32 v195, 0xc0135761, v195
	v_mul_f32_e32 v196, 0xc0135761, v196
	v_fma_f32 v197, v23, v197, v23
	v_mul_f32_e32 v138, 0xc0135761, v138
	v_mul_f32_e32 v149, 0xc0135761, v149
	v_fma_f32 v158, v30, v158, v30
	v_fma_f32 v159, v31, v159, v31
	v_exp_f32_e32 v194, v194
	v_mul_f32_e32 v197, 0xc0135761, v197
	v_mul_f32_e32 v158, 0xc0135761, v158
	v_mul_f32_e32 v159, 0xc0135761, v159
	v_exp_f32_e32 v195, v195
	v_exp_f32_e32 v196, v196
	v_exp_f32_e32 v138, v138
	v_exp_f32_e32 v149, v149
	v_exp_f32_e32 v197, v197
	v_exp_f32_e32 v158, v158
	v_exp_f32_e32 v159, v159
	v_add_f32_e32 v194, 1.0, v194
	v_rcp_f32_e32 v194, v194
	v_add_f32_e32 v195, 1.0, v195
	v_add_f32_e32 v196, 1.0, v196
	v_add_f32_e32 v138, 1.0, v138
	v_add_f32_e32 v149, 1.0, v149
	v_rcp_f32_e32 v195, v195
	v_rcp_f32_e32 v196, v196
	v_add_f32_e32 v197, 1.0, v197
	v_rcp_f32_e32 v138, v138
	v_rcp_f32_e32 v149, v149
	v_add_f32_e32 v158, 1.0, v158
	v_add_f32_e32 v159, 1.0, v159
	v_rcp_f32_e32 v197, v197
	v_rcp_f32_e32 v158, v158
	v_rcp_f32_e32 v159, v159
	v_mul_f32_e32 v198, v20, v194
	v_mul_f32_e32 v199, v21, v195
	v_mul_f32_e32 v200, v22, v196
	v_cvt_pk_bf16_f32 v196, v198, v199
	v_add_co_u32_e32 v198, vcc, s92, v156
	v_mul_f32_e32 v138, v28, v138
	v_mul_f32_e32 v149, v29, v149
	v_mul_f32_e32 v197, v23, v197
	v_cvt_pk_bf16_f32 v194, v138, v149
	v_addc_co_u32_e32 v199, vcc, 0, v157, vcc
	v_mul_f32_e32 v158, v30, v158
	v_mul_f32_e32 v159, v31, v159
	v_cvt_pk_bf16_f32 v195, v158, v159
	v_cvt_pk_bf16_f32 v197, v200, v197
	global_store_dwordx4 v[198:199], v[194:197], off
; DI unsigned cvt_pk_bf16(float lo, float hi) { unsigned r; asm("v_cvt_pk_bf16_f32 %0, %1, %2" : "=v"(r) : "v"(lo), "v"(hi)); return r; }
; DI float gelu_tanh(float x) { const float y = 1.5957691216f * (x + 0.044715f * x * x * x); return x * sigmoidf_(y); }
; DI float sigmoidf_(float x) { return __builtin_amdgcn_rcpf(1.0f + __expf(-x)); }
;     DI void operator()(const AccT& acc, const Unit& u, int wr, int wc, int fr, int fq) const {
;     ...
;             const int col0 = (u.pn - 32) * 256 + wc * 32 + 8 * fq;
; #pragma unroll
;             for (int ai = 0; ai < 2; ++ai)
; #pragma unroll
;                 for (int m = 0; m < 4; ++m)
; #pragma unroll
;                     for (int bj = 0; bj < 2; ++bj) {
;                         float y[8];
; #pragma unroll
;                         for (int n = 0; n < 2; ++n)
; #pragma unroll
;                             for (int j = 0; j < 4; ++j) y[n * 4 + j] = gelu_tanh(acc[ai][bj][m][n][j]);
;                         u32x4 w; w.x = cvt_pk_bf16(y[0], y[1]); w.y = cvt_pk_bf16(y[2], y[3]); w.z = cvt_pk_bf16(y[4], y[5]); w.w = cvt_pk_bf16(y[6], y[7]);
;                         *(u32x4*)(V + (size_t)(row0 + ai * 128 + m * 16) * EI + col0 + bj * 128) = w;
;                     }
	v_mul_f32_e32 v138, 0x3d372713, v24
	v_mul_f32_e32 v149, 0x3d372713, v25
	v_mul_f32_e32 v194, 0x3d372713, v26
	v_mul_f32_e32 v194, v26, v194
	v_fma_f32 v194, v26, v194, v26
	v_mul_f32_e32 v194, 0xc0135761, v194
	v_exp_f32_e32 v194, v194
	v_mul_f32_e32 v195, 0x3d372713, v27
	v_mul_f32_e32 v195, v27, v195
	v_fma_f32 v195, v27, v195, v27
	v_mul_f32_e32 v195, 0xc0135761, v195
	v_add_f32_e32 v194, 1.0, v194
	v_rcp_f32_e32 v194, v194
	v_exp_f32_e32 v195, v195
	v_mul_f32_e32 v197, 0x3d372713, v17
	v_mul_f32_e32 v197, v17, v197
	v_mul_f32_e32 v196, v26, v194
	v_add_f32_e32 v194, 1.0, v195
	v_mul_f32_e32 v195, 0x3d372713, v16
	v_mul_f32_e32 v195, v16, v195
	v_fma_f32 v195, v16, v195, v16
	v_fma_f32 v197, v17, v197, v17
	v_mul_f32_e32 v195, 0xc0135761, v195
	v_mul_f32_e32 v197, 0xc0135761, v197
	v_rcp_f32_e32 v194, v194
	v_exp_f32_e32 v195, v195
	v_exp_f32_e32 v197, v197
	v_mul_f32_e32 v138, v24, v138
	v_mul_f32_e32 v198, v27, v194
	v_add_f32_e32 v194, 1.0, v195
	v_add_f32_e32 v195, 1.0, v197
	v_mul_f32_e32 v197, 0x3d372713, v18
	v_mul_f32_e32 v149, v25, v149
	v_mul_f32_e32 v197, v18, v197
	v_mul_f32_e32 v199, 0x3d372713, v19
	v_fma_f32 v138, v24, v138, v24
	v_fma_f32 v149, v25, v149, v25
	v_fma_f32 v197, v18, v197, v18
	v_mul_f32_e32 v199, v19, v199
	v_mul_f32_e32 v138, 0xc0135761, v138
	v_mul_f32_e32 v149, 0xc0135761, v149
	v_mul_f32_e32 v197, 0xc0135761, v197
	v_fma_f32 v199, v19, v199, v19
	v_mul_f32_e32 v199, 0xc0135761, v199
	v_exp_f32_e32 v138, v138
	v_exp_f32_e32 v149, v149
	v_exp_f32_e32 v197, v197
	v_exp_f32_e32 v199, v199
	v_add_f32_e32 v138, 1.0, v138
	v_add_f32_e32 v149, 1.0, v149
	v_add_f32_e32 v197, 1.0, v197
	v_rcp_f32_e32 v138, v138
	v_rcp_f32_e32 v149, v149
	v_rcp_f32_e32 v194, v194
	v_rcp_f32_e32 v195, v195
	v_rcp_f32_e32 v197, v197
	v_add_f32_e32 v199, 1.0, v199
	v_rcp_f32_e32 v199, v199
	v_lshl_add_u64 v[158:159], v[156:157], 0, s[52:53]
	v_mul_f32_e32 v138, v24, v138
	v_mul_f32_e32 v149, v25, v149
	v_mul_f32_e32 v200, v16, v194
	v_mul_f32_e32 v201, v17, v195
	v_mul_f32_e32 v197, v18, v197
	v_cvt_pk_bf16_f32 v194, v138, v149
	v_cvt_pk_bf16_f32 v195, v196, v198
	v_mul_f32_e32 v199, v19, v199
	v_cvt_pk_bf16_f32 v196, v200, v201
	v_cvt_pk_bf16_f32 v197, v197, v199
	global_store_dwordx4 v[158:159], v[194:197], off offset:256
	v_mul_f32_e32 v138, 0x3d372713, v12
	v_mul_f32_e32 v149, 0x3d372713, v13
	v_mul_f32_e32 v194, 0x3d372713, v4
	v_mul_f32_e32 v195, 0x3d372713, v5
	v_mul_f32_e32 v194, v4, v194
	v_mul_f32_e32 v195, v5, v195
	v_mul_f32_e32 v196, 0x3d372713, v6
	v_fma_f32 v194, v4, v194, v4
	v_fma_f32 v195, v5, v195, v5
	v_mul_f32_e32 v196, v6, v196
	v_mul_f32_e32 v197, 0x3d372713, v7
	v_mul_f32_e32 v158, 0x3d372713, v14
	v_mul_f32_e32 v159, 0x3d372713, v15
	v_mul_f32_e32 v194, 0xc0135761, v194
	v_mul_f32_e32 v195, 0xc0135761, v195
	v_fma_f32 v196, v6, v196, v6
	v_mul_f32_e32 v197, v7, v197
	v_mul_f32_e32 v138, v12, v138
	v_mul_f32_e32 v149, v13, v149
	v_mul_f32_e32 v158, v14, v158
	v_mul_f32_e32 v159, v15, v159
	v_mul_f32_e32 v196, 0xc0135761, v196
	v_fma_f32 v197, v7, v197, v7
	v_fma_f32 v138, v12, v138, v12
	v_fma_f32 v149, v13, v149, v13
	v_fma_f32 v158, v14, v158, v14
	v_fma_f32 v159, v15, v159, v15
	v_exp_f32_e32 v194, v194
	v_exp_f32_e32 v195, v195
	v_mul_f32_e32 v197, 0xc0135761, v197
	v_mul_f32_e32 v138, 0xc0135761, v138
	v_mul_f32_e32 v149, 0xc0135761, v149
	v_mul_f32_e32 v158, 0xc0135761, v158
	v_mul_f32_e32 v159, 0xc0135761, v159
	v_exp_f32_e32 v196, v196
	v_exp_f32_e32 v197, v197
	v_exp_f32_e32 v138, v138
	v_exp_f32_e32 v149, v149
	v_exp_f32_e32 v158, v158
	v_exp_f32_e32 v159, v159
	v_add_f32_e32 v194, 1.0, v194
	v_add_f32_e32 v195, 1.0, v195
	v_rcp_f32_e32 v194, v194
	v_rcp_f32_e32 v195, v195
	v_add_f32_e32 v196, 1.0, v196
	v_rcp_f32_e32 v196, v196
	v_add_f32_e32 v197, 1.0, v197
	v_add_f32_e32 v138, 1.0, v138
	v_add_f32_e32 v149, 1.0, v149
	v_add_f32_e32 v158, 1.0, v158
	v_add_f32_e32 v159, 1.0, v159
	v_rcp_f32_e32 v197, v197
	v_rcp_f32_e32 v138, v138
	v_rcp_f32_e32 v149, v149
	v_rcp_f32_e32 v158, v158
	v_rcp_f32_e32 v159, v159
	v_mul_f32_e32 v198, v4, v194
	v_mul_f32_e32 v199, v5, v195
	v_mul_f32_e32 v200, v6, v196
	v_cvt_pk_bf16_f32 v196, v198, v199
	v_lshl_add_u64 v[198:199], v[156:157], 0, s[54:55]
	v_add_co_u32_e32 v156, vcc, s93, v156
	v_mul_f32_e32 v197, v7, v197
	s_nop 0
	v_addc_co_u32_e32 v157, vcc, 0, v157, vcc
	v_mul_f32_e32 v138, v12, v138
	v_mul_f32_e32 v149, v13, v149
	v_mul_f32_e32 v158, v14, v158
	v_mul_f32_e32 v159, v15, v159
	v_cvt_pk_bf16_f32 v194, v138, v149
	v_cvt_pk_bf16_f32 v195, v158, v159
	v_cvt_pk_bf16_f32 v197, v200, v197
	global_store_dwordx4 v[156:157], v[194:197], off
	v_mul_f32_e32 v156, 0x3d372713, v10
	v_mul_f32_e32 v156, v10, v156
	v_fma_f32 v156, v10, v156, v10
	v_mul_f32_e32 v156, 0xc0135761, v156
	v_exp_f32_e32 v156, v156
	v_mul_f32_e32 v157, 0x3d372713, v11
	v_mul_f32_e32 v157, v11, v157
	v_fma_f32 v157, v11, v157, v11
	v_mul_f32_e32 v157, 0xc0135761, v157
	v_add_f32_e32 v156, 1.0, v156
	v_rcp_f32_e32 v156, v156
	v_exp_f32_e32 v157, v157
	v_mul_f32_e32 v159, 0x3d372713, v1
	v_mul_f32_e32 v159, v1, v159
	v_mul_f32_e32 v158, v10, v156
	v_add_f32_e32 v156, 1.0, v157
	v_mul_f32_e32 v157, 0x3d372713, v0
	v_mul_f32_e32 v157, v0, v157
	v_fma_f32 v157, v0, v157, v0
	v_fma_f32 v159, v1, v159, v1
	v_mul_f32_e32 v157, 0xc0135761, v157
	v_mul_f32_e32 v159, 0xc0135761, v159
	v_rcp_f32_e32 v156, v156
	v_exp_f32_e32 v157, v157
	v_exp_f32_e32 v159, v159
	v_mul_f32_e32 v138, 0x3d372713, v8
	v_mul_f32_e32 v194, v11, v156
	v_add_f32_e32 v156, 1.0, v157
	v_add_f32_e32 v157, 1.0, v159
	v_mul_f32_e32 v159, 0x3d372713, v2
	v_mul_f32_e32 v149, 0x3d372713, v9
	v_mul_f32_e32 v159, v2, v159
	v_mul_f32_e32 v195, 0x3d372713, v3
	v_mul_f32_e32 v138, v8, v138
	v_mul_f32_e32 v149, v9, v149
	v_fma_f32 v159, v2, v159, v2
	v_mul_f32_e32 v195, v3, v195
	v_fma_f32 v138, v8, v138, v8
	v_fma_f32 v149, v9, v149, v9
	v_mul_f32_e32 v159, 0xc0135761, v159
	v_fma_f32 v195, v3, v195, v3
	v_mul_f32_e32 v138, 0xc0135761, v138
	v_mul_f32_e32 v149, 0xc0135761, v149
	v_mul_f32_e32 v195, 0xc0135761, v195
	v_exp_f32_e32 v159, v159
	v_exp_f32_e32 v138, v138
	v_exp_f32_e32 v149, v149
	v_exp_f32_e32 v195, v195
	v_add_f32_e32 v159, 1.0, v159
	v_add_f32_e32 v138, 1.0, v138
	v_add_f32_e32 v149, 1.0, v149
	v_rcp_f32_e32 v159, v159
	v_add_f32_e32 v195, 1.0, v195
	v_rcp_f32_e32 v138, v138
	v_rcp_f32_e32 v149, v149
	v_rcp_f32_e32 v156, v156
	v_rcp_f32_e32 v157, v157
	v_rcp_f32_e32 v195, v195
	v_mul_f32_e32 v159, v2, v159
	v_mul_f32_e32 v138, v8, v138
	v_mul_f32_e32 v149, v9, v149
	v_mul_f32_e32 v196, v0, v156
	v_mul_f32_e32 v197, v1, v157
	v_mul_f32_e32 v195, v3, v195
	v_cvt_pk_bf16_f32 v156, v138, v149
	v_cvt_pk_bf16_f32 v157, v158, v194
	v_cvt_pk_bf16_f32 v158, v196, v197
	v_cvt_pk_bf16_f32 v159, v159, v195
	global_store_dwordx4 v[198:199], v[156:159], off offset:256
	s_cbranch_execnz .LBB0_163
